# GEMM unit start: 128 accumulator clears per unit merged into 64 v_mov_b64 (all four GEMM instantiations), on top of k45
# baseline (speedup 1.0000x reference)
.LBB0_236:
	s_ashr_i32 s29, s28, 31
	s_lshl_b64 s[6:7], s[28:29], 20
	v_readlane_b32 s36, v249, 35
	v_readlane_b32 s37, v249, 36
	s_add_u32 s36, s36, s6
	s_addc_u32 s37, s37, s7
	s_and_b64 s[6:7], s[38:39], exec
	s_cselect_b32 s29, s9, s37
	s_cselect_b32 s31, s8, s36
	s_ashr_i32 s6, s28, 3
	s_ashr_i32 s7, s6, 31
	s_lshl_b64 s[6:7], s[6:7], 2
	s_add_u32 s40, s70, s6
	v_mov_b64_e32 v[30:31], 0
	v_mov_b32_e32 v165, v5
	v_mov_b32_e32 v166, v4
	v_lshl_add_u64 v[92:93], v[2:3], 2, s[70:71]
	s_addc_u32 s41, s71, s7
	s_mov_b32 s80, 0
	v_mov_b64_e32 v[32:33], 0
	v_mov_b64_e32 v[38:39], 0
	v_mov_b64_e32 v[40:41], 0
	v_mov_b64_e32 v[74:75], 0
	v_mov_b64_e32 v[76:77], 0
	v_mov_b64_e32 v[78:79], 0
	v_mov_b64_e32 v[80:81], 0
	v_mov_b64_e32 v[82:83], 0
	v_mov_b64_e32 v[84:85], 0
	v_mov_b64_e32 v[86:87], 0
	v_mov_b64_e32 v[88:89], 0
	v_mov_b64_e32 v[98:99], 0
	v_mov_b64_e32 v[100:101], 0
	v_mov_b64_e32 v[102:103], 0
	v_mov_b64_e32 v[104:105], 0
	v_mov_b64_e32 v[2:3], 0
	v_mov_b64_e32 v[4:5], 0
	v_mov_b64_e32 v[6:7], 0
	v_mov_b64_e32 v[8:9], 0
	v_mov_b64_e32 v[10:11], 0
	v_mov_b64_e32 v[12:13], 0
	v_mov_b64_e32 v[14:15], 0
	v_mov_b64_e32 v[16:17], 0
	v_mov_b64_e32 v[18:19], 0
	v_mov_b64_e32 v[20:21], 0
	v_mov_b64_e32 v[22:23], 0
	v_mov_b64_e32 v[24:25], 0
	v_mov_b64_e32 v[26:27], 0
	v_mov_b64_e32 v[28:29], 0
	v_mov_b64_e32 v[34:35], 0
	v_mov_b64_e32 v[36:37], 0
	v_mov_b64_e32 v[106:107], 0
	v_mov_b64_e32 v[108:109], 0
	v_mov_b64_e32 v[110:111], 0
	v_mov_b64_e32 v[112:113], 0
	v_mov_b64_e32 v[114:115], 0
	v_mov_b64_e32 v[116:117], 0
	v_mov_b64_e32 v[118:119], 0
	v_mov_b64_e32 v[120:121], 0
	v_mov_b64_e32 v[122:123], 0
	v_mov_b64_e32 v[124:125], 0
	v_mov_b64_e32 v[126:127], 0
	v_mov_b64_e32 v[128:129], 0
	v_mov_b64_e32 v[130:131], 0
	v_mov_b64_e32 v[132:133], 0
	v_mov_b64_e32 v[134:135], 0
	v_mov_b64_e32 v[136:137], 0
	v_mov_b64_e32 v[42:43], 0
	v_mov_b64_e32 v[44:45], 0
	v_mov_b64_e32 v[46:47], 0
	v_mov_b64_e32 v[48:49], 0
	v_mov_b64_e32 v[50:51], 0
	v_mov_b64_e32 v[52:53], 0
	v_mov_b64_e32 v[54:55], 0
	v_mov_b64_e32 v[56:57], 0
	v_mov_b64_e32 v[58:59], 0
	v_mov_b64_e32 v[60:61], 0
	v_mov_b64_e32 v[62:63], 0
	v_mov_b64_e32 v[64:65], 0
	v_mov_b64_e32 v[66:67], 0
	v_mov_b64_e32 v[68:69], 0
	v_mov_b64_e32 v[70:71], 0
	v_mov_b64_e32 v[72:73], 0

.LBB0_710:
	s_ashr_i32 s21, s20, 31
	s_lshl_b64 s[22:23], s[20:21], 20
	v_readlane_b32 s24, v249, 41
	v_readlane_b32 s25, v249, 42
	s_add_u32 s22, s24, s22
	s_addc_u32 s23, s25, s23
	s_and_b64 s[24:25], s[28:29], exec
	s_cselect_b32 s5, s23, s7
	s_cselect_b32 s21, s22, s6
	s_ashr_i32 s19, s18, 31
	s_lshl_b64 s[24:25], s[18:19], 20
	v_readlane_b32 s56, v249, 35
	v_readlane_b32 s57, v249, 36
	s_add_u32 s24, s56, s24
	s_addc_u32 s25, s57, s25
	s_and_b64 s[28:29], s[28:29], exec
	s_cselect_b32 s19, s25, s27
	s_cselect_b32 s51, s24, s26
	s_add_u32 s6, s6, 0x80080
	s_addc_u32 s7, s7, 0
	s_add_u32 s56, s26, 0x100
	s_waitcnt vmcnt(0)
	v_mov_b64_e32 v[30:31], 0
	s_addc_u32 s57, s27, 0
	s_mov_b32 s58, -2
	v_mov_b64_e32 v[32:33], 0
	v_mov_b64_e32 v[38:39], 0
	v_mov_b64_e32 v[40:41], 0
	v_mov_b64_e32 v[74:75], 0
	v_mov_b64_e32 v[76:77], 0
	v_mov_b64_e32 v[78:79], 0
	v_mov_b64_e32 v[80:81], 0
	v_mov_b64_e32 v[82:83], 0
	v_mov_b64_e32 v[84:85], 0
	v_mov_b64_e32 v[86:87], 0
	v_mov_b64_e32 v[88:89], 0
	v_mov_b64_e32 v[90:91], 0
	v_mov_b64_e32 v[92:93], 0
	v_mov_b64_e32 v[94:95], 0
	v_mov_b64_e32 v[96:97], 0
	v_mov_b64_e32 v[2:3], 0
	v_mov_b64_e32 v[4:5], 0
	v_mov_b64_e32 v[6:7], 0
	v_mov_b64_e32 v[8:9], 0
	v_mov_b64_e32 v[10:11], 0
	v_mov_b64_e32 v[12:13], 0
	v_mov_b64_e32 v[14:15], 0
	v_mov_b64_e32 v[16:17], 0
	v_mov_b64_e32 v[18:19], 0
	v_mov_b64_e32 v[20:21], 0
	v_mov_b64_e32 v[22:23], 0
	v_mov_b64_e32 v[24:25], 0
	v_mov_b64_e32 v[26:27], 0
	v_mov_b64_e32 v[28:29], 0
	v_mov_b64_e32 v[34:35], 0
	v_mov_b64_e32 v[36:37], 0
	v_mov_b64_e32 v[106:107], 0
	v_mov_b64_e32 v[108:109], 0
	v_mov_b64_e32 v[110:111], 0
	v_mov_b64_e32 v[112:113], 0
	v_mov_b64_e32 v[114:115], 0
	v_mov_b64_e32 v[116:117], 0
	v_mov_b64_e32 v[118:119], 0
	v_mov_b64_e32 v[120:121], 0
	v_mov_b64_e32 v[122:123], 0
	v_mov_b64_e32 v[124:125], 0
	v_mov_b64_e32 v[126:127], 0
	v_mov_b64_e32 v[128:129], 0
	v_mov_b64_e32 v[130:131], 0
	v_mov_b64_e32 v[132:133], 0
	v_mov_b64_e32 v[134:135], 0
	v_mov_b64_e32 v[136:137], 0
	v_mov_b64_e32 v[42:43], 0
	v_mov_b64_e32 v[44:45], 0
	v_mov_b64_e32 v[46:47], 0
	v_mov_b64_e32 v[48:49], 0
	v_mov_b64_e32 v[50:51], 0
	v_mov_b64_e32 v[52:53], 0
	v_mov_b64_e32 v[54:55], 0
	v_mov_b64_e32 v[56:57], 0
	v_mov_b64_e32 v[58:59], 0
	v_mov_b64_e32 v[60:61], 0
	v_mov_b64_e32 v[62:63], 0
	v_mov_b64_e32 v[64:65], 0
	v_mov_b64_e32 v[66:67], 0
	v_mov_b64_e32 v[68:69], 0
	v_mov_b64_e32 v[70:71], 0
	v_mov_b64_e32 v[72:73], 0

.LBB0_951:
	s_lshl_b32 s44, s22, 8
	s_lshl_b32 s45, s23, 8
	s_or_b32 s46, s45, s35
	s_add_i32 s47, s44, s34
	s_add_u32 s48, s20, 0x100
	v_mov_b64_e32 v[2:3], 0
	v_lshl_add_u64 v[146:147], s[18:19], 0, v[138:139]
	v_lshl_add_u64 v[148:149], s[18:19], 0, v[140:141]
	s_addc_u32 s49, s21, 0
	s_mov_b32 s50, -2
	s_mov_b64 s[20:21], 0
	v_mov_b64_e32 v[4:5], 0
	v_mov_b64_e32 v[6:7], 0
	v_mov_b64_e32 v[8:9], 0
	v_mov_b64_e32 v[14:15], 0
	v_mov_b64_e32 v[16:17], 0
	v_mov_b64_e32 v[22:23], 0
	v_mov_b64_e32 v[24:25], 0
	v_mov_b64_e32 v[30:31], 0
	v_mov_b64_e32 v[32:33], 0
	v_mov_b64_e32 v[38:39], 0
	v_mov_b64_e32 v[40:41], 0
	v_mov_b64_e32 v[46:47], 0
	v_mov_b64_e32 v[48:49], 0
	v_mov_b64_e32 v[54:55], 0
	v_mov_b64_e32 v[56:57], 0
	v_mov_b64_e32 v[10:11], 0
	v_mov_b64_e32 v[12:13], 0
	v_mov_b64_e32 v[18:19], 0
	v_mov_b64_e32 v[20:21], 0
	v_mov_b64_e32 v[26:27], 0
	v_mov_b64_e32 v[28:29], 0
	v_mov_b64_e32 v[34:35], 0
	v_mov_b64_e32 v[36:37], 0
	v_mov_b64_e32 v[42:43], 0
	v_mov_b64_e32 v[44:45], 0
	v_mov_b64_e32 v[50:51], 0
	v_mov_b64_e32 v[52:53], 0
	v_mov_b64_e32 v[58:59], 0
	v_mov_b64_e32 v[60:61], 0
	v_mov_b64_e32 v[62:63], 0
	v_mov_b64_e32 v[64:65], 0
	v_mov_b64_e32 v[66:67], 0
	v_mov_b64_e32 v[68:69], 0
	v_mov_b64_e32 v[70:71], 0
	v_mov_b64_e32 v[72:73], 0
	v_mov_b64_e32 v[78:79], 0
	v_mov_b64_e32 v[80:81], 0
	v_mov_b64_e32 v[86:87], 0
	v_mov_b64_e32 v[88:89], 0
	v_mov_b64_e32 v[94:95], 0
	v_mov_b64_e32 v[96:97], 0
	v_mov_b64_e32 v[102:103], 0
	v_mov_b64_e32 v[104:105], 0
	v_mov_b64_e32 v[110:111], 0
	v_mov_b64_e32 v[112:113], 0
	v_mov_b64_e32 v[118:119], 0
	v_mov_b64_e32 v[120:121], 0
	v_mov_b64_e32 v[74:75], 0
	v_mov_b64_e32 v[76:77], 0
	v_mov_b64_e32 v[82:83], 0
	v_mov_b64_e32 v[84:85], 0
	v_mov_b64_e32 v[90:91], 0
	v_mov_b64_e32 v[92:93], 0
	v_mov_b64_e32 v[98:99], 0
	v_mov_b64_e32 v[100:101], 0
	v_mov_b64_e32 v[106:107], 0
	v_mov_b64_e32 v[108:109], 0
	v_mov_b64_e32 v[114:115], 0
	v_mov_b64_e32 v[116:117], 0
	v_mov_b64_e32 v[122:123], 0
	v_mov_b64_e32 v[124:125], 0
	v_mov_b64_e32 v[126:127], 0
	v_mov_b64_e32 v[128:129], 0
	s_branch .LBB0_953

.LBB0_1032:
	s_ashr_i32 s25, s24, 31
	s_lshl_b64 s[26:27], s[24:25], 20
	s_add_u32 s26, s8, s26
	s_addc_u32 s27, s9, s27
	s_and_b64 s[28:29], s[0:1], exec
	s_cselect_b32 s25, s27, s35
	s_cselect_b32 s52, s26, s34
	s_ashr_i32 s23, s22, 31
	s_lshl_b64 s[28:29], s[22:23], 20
	v_readlane_b32 s38, v249, 39
	v_readlane_b32 s39, v249, 40
	s_add_u32 s28, s38, s28
	s_addc_u32 s29, s39, s29
	s_and_b64 s[38:39], s[0:1], exec
	s_cselect_b32 s23, s29, s37
	s_cselect_b32 s53, s28, s36
	s_add_u32 s34, s34, 0x80080
	s_addc_u32 s35, s35, 0
	s_add_u32 s54, s36, 0x100
	v_mov_b64_e32 v[0:1], 0
	s_addc_u32 s55, s37, 0
	s_mov_b32 s56, -2
	s_lshl_b32 s98, s30, 21
	s_lshl_b32 s99, s51, 10
	s_add_i32 s98, s98, s99
	v_readlane_b32 s100, v249, 12
	v_readlane_b32 s101, v249, 13
	v_add_u32_e32 v246, s98, v247
	v_mov_b64_e32 v[2:3], 0
	v_mov_b64_e32 v[4:5], 0
	v_mov_b64_e32 v[6:7], 0
	v_mov_b64_e32 v[8:9], 0
	v_mov_b64_e32 v[10:11], 0
	v_mov_b64_e32 v[20:21], 0
	v_mov_b64_e32 v[22:23], 0
	v_mov_b64_e32 v[24:25], 0
	v_mov_b64_e32 v[26:27], 0
	v_mov_b64_e32 v[36:37], 0
	v_mov_b64_e32 v[38:39], 0
	v_mov_b64_e32 v[40:41], 0
	v_mov_b64_e32 v[42:43], 0
	v_mov_b64_e32 v[52:53], 0
	v_mov_b64_e32 v[54:55], 0
	v_mov_b64_e32 v[12:13], 0
	v_mov_b64_e32 v[14:15], 0
	v_mov_b64_e32 v[16:17], 0
	v_mov_b64_e32 v[18:19], 0
	v_mov_b64_e32 v[28:29], 0
	v_mov_b64_e32 v[30:31], 0
	v_mov_b64_e32 v[32:33], 0
	v_mov_b64_e32 v[34:35], 0
	v_mov_b64_e32 v[44:45], 0
	v_mov_b64_e32 v[46:47], 0
	v_mov_b64_e32 v[48:49], 0
	v_mov_b64_e32 v[50:51], 0
	v_mov_b64_e32 v[56:57], 0
	v_mov_b64_e32 v[58:59], 0
	v_mov_b64_e32 v[60:61], 0
	v_mov_b64_e32 v[62:63], 0
	v_mov_b64_e32 v[64:65], 0
	v_mov_b64_e32 v[66:67], 0
	v_mov_b64_e32 v[68:69], 0
	v_mov_b64_e32 v[70:71], 0
	v_mov_b64_e32 v[72:73], 0
	v_mov_b64_e32 v[74:75], 0
	v_mov_b64_e32 v[84:85], 0
	v_mov_b64_e32 v[86:87], 0
	v_mov_b64_e32 v[88:89], 0
	v_mov_b64_e32 v[90:91], 0
	v_mov_b64_e32 v[100:101], 0
	v_mov_b64_e32 v[102:103], 0
	v_mov_b64_e32 v[104:105], 0
	v_mov_b64_e32 v[106:107], 0
	v_mov_b64_e32 v[116:117], 0
	v_mov_b64_e32 v[118:119], 0
	v_mov_b64_e32 v[76:77], 0
	v_mov_b64_e32 v[78:79], 0
	v_mov_b64_e32 v[80:81], 0
	v_mov_b64_e32 v[82:83], 0
	v_mov_b64_e32 v[92:93], 0
	v_mov_b64_e32 v[94:95], 0
	v_mov_b64_e32 v[96:97], 0
	v_mov_b64_e32 v[98:99], 0
	v_mov_b64_e32 v[108:109], 0
	v_mov_b64_e32 v[110:111], 0
	v_mov_b64_e32 v[112:113], 0
	v_mov_b64_e32 v[114:115], 0
	v_mov_b64_e32 v[120:121], 0
	v_mov_b64_e32 v[122:123], 0
	v_mov_b64_e32 v[124:125], 0
	v_mov_b64_e32 v[126:127], 0
